# stack25 + P3/P9 GEMM epilogues: eight rowss loads issued up front, one wait, per-row vmcnt(0) drains removed
# speedup vs baseline: 1.0046x; 1.0046x over previous
.LBB0_395:
	v_lshl_or_b32 v146, s16, 8, v155
	v_ashrrev_i32_e32 v147, 31, v146
	v_lshl_add_u64 v[150:151], v[146:147], 2, s[12:13]
	global_load_dword v147, v[150:151], off
	global_load_dword v200, v[150:151], off offset:64
	global_load_dword v201, v[150:151], off offset:128
	global_load_dword v202, v[150:151], off offset:192
	global_load_dword v203, v[150:151], off offset:512
	global_load_dword v204, v[150:151], off offset:576
	global_load_dword v205, v[150:151], off offset:640
	global_load_dword v206, v[150:151], off offset:704
	s_add_u32 s40, s40, s57
	s_addc_u32 s41, s41, 0
	v_mad_i64_i32 v[160:161], s[42:43], s36, v146, 0
	v_lshl_add_u64 v[148:149], s[40:41], 0, v[136:137]
	s_lshl_b32 s16, s38, 1
	v_lshl_add_u64 v[160:161], v[160:161], 1, v[148:149]
	v_lshl_add_u64 v[164:165], v[160:161], 0, s[16:17]
	s_andn2_b64 vcc, exec, s[2:3]
	s_mov_b64 s[2:3], -1
	s_waitcnt vmcnt(0)
	v_fmamk_f32 v147, v147, 0x3a000000, v159
	v_rsq_f32_e32 v162, v147
	s_nop 0
	v_pk_mul_f32 v[126:127], v[126:127], v[162:163] op_sel_hi:[1,0]
	v_pk_mul_f32 v[124:125], v[124:125], v[162:163] op_sel_hi:[1,0]
	v_pk_mul_f32 v[122:123], v[122:123], v[162:163] op_sel_hi:[1,0]
	v_pk_mul_f32 v[120:121], v[120:121], v[162:163] op_sel_hi:[1,0]
	v_pk_mul_f32 v[118:119], v[118:119], v[162:163] op_sel_hi:[1,0]
	v_pk_mul_f32 v[116:117], v[116:117], v[162:163] op_sel_hi:[1,0]
	v_pk_mul_f32 v[166:167], v[114:115], v[162:163] op_sel_hi:[1,0]
	v_pk_mul_f32 v[162:163], v[112:113], v[162:163] op_sel_hi:[1,0]
	v_cvt_pk_bf16_f32 v112, v124, v125
	v_cvt_pk_bf16_f32 v113, v126, v127
	v_cvt_pk_bf16_f32 v114, v120, v121
	v_cvt_pk_bf16_f32 v115, v122, v123
	global_store_dwordx4 v[160:161], v[112:115], off
	s_nop 1
	v_cvt_pk_bf16_f32 v112, v116, v117
	v_cvt_pk_bf16_f32 v113, v118, v119
	v_cvt_pk_bf16_f32 v114, v162, v163
	v_cvt_pk_bf16_f32 v115, v166, v167
	global_store_dwordx4 v[164:165], v[112:115], off
	s_nop 1
	s_nop 0
	v_or_b32_e32 v113, 16, v146
	v_mad_i64_i32 v[114:115], s[38:39], s36, v113, 0
	v_lshl_add_u64 v[114:115], v[114:115], 1, v[148:149]
	v_lshl_add_u64 v[116:117], v[114:115], 0, s[16:17]
	v_mov_b32_e32 v112, v200
	v_fmamk_f32 v112, v112, 0x3a000000, v159
	v_rsq_f32_e32 v112, v112
	s_nop 0
	v_pk_mul_f32 v[110:111], v[110:111], v[112:113] op_sel_hi:[1,0]
	v_pk_mul_f32 v[108:109], v[108:109], v[112:113] op_sel_hi:[1,0]
	v_pk_mul_f32 v[106:107], v[106:107], v[112:113] op_sel_hi:[1,0]
	v_pk_mul_f32 v[104:105], v[104:105], v[112:113] op_sel_hi:[1,0]
	v_pk_mul_f32 v[102:103], v[102:103], v[112:113] op_sel_hi:[1,0]
	v_pk_mul_f32 v[100:101], v[100:101], v[112:113] op_sel_hi:[1,0]
	v_pk_mul_f32 v[118:119], v[98:99], v[112:113] op_sel_hi:[1,0]
	v_pk_mul_f32 v[112:113], v[96:97], v[112:113] op_sel_hi:[1,0]
	v_cvt_pk_bf16_f32 v96, v108, v109
	v_cvt_pk_bf16_f32 v97, v110, v111
	v_cvt_pk_bf16_f32 v98, v104, v105
	v_cvt_pk_bf16_f32 v99, v106, v107
	global_store_dwordx4 v[114:115], v[96:99], off
	s_nop 1
	v_cvt_pk_bf16_f32 v96, v100, v101
	v_cvt_pk_bf16_f32 v97, v102, v103
	v_cvt_pk_bf16_f32 v98, v112, v113
	v_cvt_pk_bf16_f32 v99, v118, v119
	global_store_dwordx4 v[116:117], v[96:99], off
	s_nop 1
	s_nop 0
	v_or_b32_e32 v97, 32, v146
	v_mad_i64_i32 v[98:99], s[38:39], s36, v97, 0
	v_lshl_add_u64 v[98:99], v[98:99], 1, v[148:149]
	v_lshl_add_u64 v[100:101], v[98:99], 0, s[16:17]
	v_mov_b32_e32 v96, v201
	v_fmamk_f32 v96, v96, 0x3a000000, v159
	v_rsq_f32_e32 v96, v96
	s_nop 0
	v_pk_mul_f32 v[94:95], v[94:95], v[96:97] op_sel_hi:[1,0]
	v_pk_mul_f32 v[92:93], v[92:93], v[96:97] op_sel_hi:[1,0]
	v_pk_mul_f32 v[90:91], v[90:91], v[96:97] op_sel_hi:[1,0]
	v_pk_mul_f32 v[88:89], v[88:89], v[96:97] op_sel_hi:[1,0]
	v_pk_mul_f32 v[86:87], v[86:87], v[96:97] op_sel_hi:[1,0]
	v_pk_mul_f32 v[84:85], v[84:85], v[96:97] op_sel_hi:[1,0]
	v_pk_mul_f32 v[102:103], v[82:83], v[96:97] op_sel_hi:[1,0]
	v_pk_mul_f32 v[96:97], v[80:81], v[96:97] op_sel_hi:[1,0]
	v_cvt_pk_bf16_f32 v80, v92, v93
	v_cvt_pk_bf16_f32 v81, v94, v95
	v_cvt_pk_bf16_f32 v82, v88, v89
	v_cvt_pk_bf16_f32 v83, v90, v91
	global_store_dwordx4 v[98:99], v[80:83], off
	s_nop 1
	v_cvt_pk_bf16_f32 v80, v84, v85
	v_cvt_pk_bf16_f32 v81, v86, v87
	v_cvt_pk_bf16_f32 v82, v96, v97
	v_cvt_pk_bf16_f32 v83, v102, v103
	global_store_dwordx4 v[100:101], v[80:83], off
	s_nop 1
	s_nop 0
	v_or_b32_e32 v81, 48, v146
	v_mad_i64_i32 v[82:83], s[38:39], s36, v81, 0
	v_lshl_add_u64 v[82:83], v[82:83], 1, v[148:149]
	v_lshl_add_u64 v[84:85], v[82:83], 0, s[16:17]
	v_mov_b32_e32 v80, v202
	v_fmamk_f32 v80, v80, 0x3a000000, v159
	v_rsq_f32_e32 v80, v80
	s_nop 0
	v_pk_mul_f32 v[78:79], v[78:79], v[80:81] op_sel_hi:[1,0]
	v_pk_mul_f32 v[76:77], v[76:77], v[80:81] op_sel_hi:[1,0]
	v_pk_mul_f32 v[74:75], v[74:75], v[80:81] op_sel_hi:[1,0]
	v_pk_mul_f32 v[72:73], v[72:73], v[80:81] op_sel_hi:[1,0]
	v_pk_mul_f32 v[70:71], v[70:71], v[80:81] op_sel_hi:[1,0]
	v_pk_mul_f32 v[68:69], v[68:69], v[80:81] op_sel_hi:[1,0]
	v_pk_mul_f32 v[86:87], v[66:67], v[80:81] op_sel_hi:[1,0]
	v_pk_mul_f32 v[80:81], v[64:65], v[80:81] op_sel_hi:[1,0]
	v_cvt_pk_bf16_f32 v64, v76, v77
	v_cvt_pk_bf16_f32 v65, v78, v79
	v_cvt_pk_bf16_f32 v66, v72, v73
	v_cvt_pk_bf16_f32 v67, v74, v75
	global_store_dwordx4 v[82:83], v[64:67], off
	s_nop 1
	v_cvt_pk_bf16_f32 v64, v68, v69
	v_cvt_pk_bf16_f32 v65, v70, v71
	v_cvt_pk_bf16_f32 v66, v80, v81
	v_cvt_pk_bf16_f32 v67, v86, v87
	global_store_dwordx4 v[84:85], v[64:67], off
	s_nop 1
	s_nop 0
	v_or_b32_e32 v65, 0x80, v146
	v_mad_i64_i32 v[66:67], s[38:39], s36, v65, 0
	v_lshl_add_u64 v[66:67], v[66:67], 1, v[148:149]
	v_lshl_add_u64 v[68:69], v[66:67], 0, s[16:17]
	v_mov_b32_e32 v64, v203
	v_fmamk_f32 v64, v64, 0x3a000000, v159
	v_rsq_f32_e32 v64, v64
	s_nop 0
	v_pk_mul_f32 v[62:63], v[62:63], v[64:65] op_sel_hi:[1,0]
	v_pk_mul_f32 v[60:61], v[60:61], v[64:65] op_sel_hi:[1,0]
	v_pk_mul_f32 v[58:59], v[58:59], v[64:65] op_sel_hi:[1,0]
	v_pk_mul_f32 v[56:57], v[56:57], v[64:65] op_sel_hi:[1,0]
	v_pk_mul_f32 v[54:55], v[54:55], v[64:65] op_sel_hi:[1,0]
	v_pk_mul_f32 v[52:53], v[52:53], v[64:65] op_sel_hi:[1,0]
	v_pk_mul_f32 v[70:71], v[50:51], v[64:65] op_sel_hi:[1,0]
	v_pk_mul_f32 v[64:65], v[48:49], v[64:65] op_sel_hi:[1,0]
	v_cvt_pk_bf16_f32 v48, v60, v61
	v_cvt_pk_bf16_f32 v49, v62, v63
	v_cvt_pk_bf16_f32 v50, v56, v57
	v_cvt_pk_bf16_f32 v51, v58, v59
	global_store_dwordx4 v[66:67], v[48:51], off
	s_nop 1
	v_cvt_pk_bf16_f32 v48, v52, v53
	v_cvt_pk_bf16_f32 v49, v54, v55
	v_cvt_pk_bf16_f32 v50, v64, v65
	v_cvt_pk_bf16_f32 v51, v70, v71
	global_store_dwordx4 v[68:69], v[48:51], off
	s_nop 1
	s_nop 0
	v_or_b32_e32 v49, 0x90, v146
	v_mad_i64_i32 v[50:51], s[38:39], s36, v49, 0
	v_lshl_add_u64 v[50:51], v[50:51], 1, v[148:149]
	v_lshl_add_u64 v[52:53], v[50:51], 0, s[16:17]
	v_mov_b32_e32 v48, v204
	v_fmamk_f32 v48, v48, 0x3a000000, v159
	v_rsq_f32_e32 v48, v48
	s_nop 0
	v_pk_mul_f32 v[46:47], v[46:47], v[48:49] op_sel_hi:[1,0]
	v_pk_mul_f32 v[44:45], v[44:45], v[48:49] op_sel_hi:[1,0]
	v_pk_mul_f32 v[42:43], v[42:43], v[48:49] op_sel_hi:[1,0]
	v_pk_mul_f32 v[40:41], v[40:41], v[48:49] op_sel_hi:[1,0]
	v_pk_mul_f32 v[38:39], v[38:39], v[48:49] op_sel_hi:[1,0]
	v_pk_mul_f32 v[36:37], v[36:37], v[48:49] op_sel_hi:[1,0]
	v_pk_mul_f32 v[54:55], v[34:35], v[48:49] op_sel_hi:[1,0]
	v_pk_mul_f32 v[48:49], v[32:33], v[48:49] op_sel_hi:[1,0]
	v_cvt_pk_bf16_f32 v32, v44, v45
	v_cvt_pk_bf16_f32 v33, v46, v47
	v_cvt_pk_bf16_f32 v34, v40, v41
	v_cvt_pk_bf16_f32 v35, v42, v43
	global_store_dwordx4 v[50:51], v[32:35], off
	s_nop 1
	v_cvt_pk_bf16_f32 v32, v36, v37
	v_cvt_pk_bf16_f32 v33, v38, v39
	v_cvt_pk_bf16_f32 v34, v48, v49
	v_cvt_pk_bf16_f32 v35, v54, v55
	global_store_dwordx4 v[52:53], v[32:35], off
	s_nop 1
	s_nop 0
	v_or_b32_e32 v33, 0xa0, v146
	v_mad_i64_i32 v[34:35], s[38:39], s36, v33, 0
	v_lshl_add_u64 v[34:35], v[34:35], 1, v[148:149]
	v_lshl_add_u64 v[36:37], v[34:35], 0, s[16:17]
	v_mov_b32_e32 v32, v205
	v_fmamk_f32 v32, v32, 0x3a000000, v159
	v_rsq_f32_e32 v32, v32
	s_nop 0
	v_pk_mul_f32 v[30:31], v[30:31], v[32:33] op_sel_hi:[1,0]
	v_pk_mul_f32 v[28:29], v[28:29], v[32:33] op_sel_hi:[1,0]
	v_pk_mul_f32 v[26:27], v[26:27], v[32:33] op_sel_hi:[1,0]
	v_pk_mul_f32 v[24:25], v[24:25], v[32:33] op_sel_hi:[1,0]
	v_pk_mul_f32 v[22:23], v[22:23], v[32:33] op_sel_hi:[1,0]
	v_pk_mul_f32 v[20:21], v[20:21], v[32:33] op_sel_hi:[1,0]
	v_pk_mul_f32 v[38:39], v[18:19], v[32:33] op_sel_hi:[1,0]
	v_pk_mul_f32 v[32:33], v[16:17], v[32:33] op_sel_hi:[1,0]
	v_cvt_pk_bf16_f32 v16, v28, v29
	v_cvt_pk_bf16_f32 v17, v30, v31
	v_cvt_pk_bf16_f32 v18, v24, v25
	v_cvt_pk_bf16_f32 v19, v26, v27
	global_store_dwordx4 v[34:35], v[16:19], off
	s_nop 1
	v_cvt_pk_bf16_f32 v16, v20, v21
	v_cvt_pk_bf16_f32 v17, v22, v23
	v_cvt_pk_bf16_f32 v18, v32, v33
	v_cvt_pk_bf16_f32 v19, v38, v39
	global_store_dwordx4 v[36:37], v[16:19], off
	s_nop 1
	s_nop 0
	v_or_b32_e32 v16, 0xb0, v146
	v_mad_i64_i32 v[16:17], s[36:37], s36, v16, 0
	v_lshl_add_u64 v[16:17], v[16:17], 1, v[148:149]
	v_lshl_add_u64 v[20:21], v[16:17], 0, s[16:17]
	v_mov_b32_e32 v18, v206
	v_fmamk_f32 v18, v18, 0x3a000000, v159
	v_rsq_f32_e32 v18, v18
	s_nop 0
	v_pk_mul_f32 v[14:15], v[14:15], v[18:19] op_sel_hi:[1,0]
	v_pk_mul_f32 v[12:13], v[12:13], v[18:19] op_sel_hi:[1,0]
	v_pk_mul_f32 v[10:11], v[10:11], v[18:19] op_sel_hi:[1,0]
	v_pk_mul_f32 v[8:9], v[8:9], v[18:19] op_sel_hi:[1,0]
	v_pk_mul_f32 v[6:7], v[6:7], v[18:19] op_sel_hi:[1,0]
	v_pk_mul_f32 v[4:5], v[4:5], v[18:19] op_sel_hi:[1,0]
	v_pk_mul_f32 v[22:23], v[2:3], v[18:19] op_sel_hi:[1,0]
	v_pk_mul_f32 v[18:19], v[0:1], v[18:19] op_sel_hi:[1,0]
	v_cvt_pk_bf16_f32 v0, v12, v13
	v_cvt_pk_bf16_f32 v1, v14, v15
	v_cvt_pk_bf16_f32 v2, v8, v9
	v_cvt_pk_bf16_f32 v3, v10, v11
	global_store_dwordx4 v[16:17], v[0:3], off
	s_nop 1
	v_cvt_pk_bf16_f32 v0, v4, v5
	v_cvt_pk_bf16_f32 v1, v6, v7
	v_cvt_pk_bf16_f32 v2, v18, v19
	v_cvt_pk_bf16_f32 v3, v22, v23
	global_store_dwordx4 v[20:21], v[0:3], off
	s_cbranch_vccnz .LBB0_383
	s_andn2_b64 vcc, exec, s[6:7]
	s_cbranch_vccnz .LBB0_382
	s_barrier
	s_branch .LBB0_382

.LBB0_1243:
	v_lshl_or_b32 v148, s36, 8, v151
	v_ashrrev_i32_e32 v149, 31, v148
	v_lshl_add_u64 v[144:145], v[148:149], 2, s[14:15]
	global_load_dword v149, v[144:145], off
	global_load_dword v224, v[144:145], off offset:64
	global_load_dword v225, v[144:145], off offset:128
	global_load_dword v226, v[144:145], off offset:192
	global_load_dword v227, v[144:145], off offset:512
	global_load_dword v228, v[144:145], off offset:576
	global_load_dword v229, v[144:145], off offset:640
	global_load_dword v230, v[144:145], off offset:704
	v_or_b32_e32 v160, 16, v148
	v_ashrrev_i32_e32 v161, 31, v160
	v_lshl_add_u64 v[164:165], v[160:161], 2, s[14:15]
	v_lshl_or_b32 v146, s11, 7, v152
	v_mov_b64_e32 v[144:145], s[12:13]
	v_ashrrev_i32_e32 v147, 31, v146
	v_mad_i64_i32 v[158:159], s[38:39], v148, s56, v[144:145]
	v_lshlrev_b64 v[146:147], 1, v[146:147]
	v_lshl_add_u64 v[158:159], v[158:159], 0, v[146:147]
	s_andn2_b64 vcc, exec, s[2:3]
	s_mov_b64 s[2:3], -1
	s_waitcnt vmcnt(0)
	v_fmamk_f32 v149, v149, 0x3a000000, v156
	v_rsq_f32_e32 v162, v149
	s_nop 0
	v_pk_mul_f32 v[122:123], v[122:123], v[162:163] op_sel_hi:[1,0]
	v_pk_mul_f32 v[126:127], v[126:127], v[162:163] op_sel_hi:[1,0]
	v_pk_mul_f32 v[124:125], v[124:125], v[162:163] op_sel_hi:[1,0]
	v_pk_mul_f32 v[120:121], v[120:121], v[162:163] op_sel_hi:[1,0]
	v_mul_f32_e32 v168, 0xbfb8aa3b, v123
	v_pk_mul_f32 v[118:119], v[118:119], v[162:163] op_sel_hi:[1,0]
	v_pk_mul_f32 v[116:117], v[116:117], v[162:163] op_sel_hi:[1,0]
	v_pk_mul_f32 v[114:115], v[114:115], v[162:163] op_sel_hi:[1,0]
	v_pk_mul_f32 v[112:113], v[112:113], v[162:163] op_sel_hi:[1,0]
	v_mul_f32_e32 v149, 0xbfb8aa3b, v124
	v_mul_f32_e32 v157, 0xbfb8aa3b, v125
	v_mul_f32_e32 v161, 0xbfb8aa3b, v126
	v_mul_f32_e32 v162, 0xbfb8aa3b, v127
	v_mul_f32_e32 v163, 0xbfb8aa3b, v120
	v_mul_f32_e32 v166, 0xbfb8aa3b, v121
	v_mul_f32_e32 v167, 0xbfb8aa3b, v122
	v_exp_f32_e32 v168, v168
	v_exp_f32_e32 v149, v149
	v_exp_f32_e32 v157, v157
	v_exp_f32_e32 v161, v161
	v_exp_f32_e32 v162, v162
	v_exp_f32_e32 v163, v163
	v_exp_f32_e32 v166, v166
	v_exp_f32_e32 v167, v167
	v_add_f32_e32 v168, 1.0, v168
	v_add_f32_e32 v149, 1.0, v149
	v_add_f32_e32 v157, 1.0, v157
	v_add_f32_e32 v161, 1.0, v161
	v_add_f32_e32 v162, 1.0, v162
	v_add_f32_e32 v163, 1.0, v163
	v_add_f32_e32 v166, 1.0, v166
	v_add_f32_e32 v167, 1.0, v167
	v_rcp_f32_e32 v168, v168
	v_rcp_f32_e32 v149, v149
	v_rcp_f32_e32 v157, v157
	v_rcp_f32_e32 v161, v161
	v_rcp_f32_e32 v162, v162
	v_rcp_f32_e32 v163, v163
	v_rcp_f32_e32 v166, v166
	v_rcp_f32_e32 v167, v167
	v_mul_f32_e32 v123, v123, v168
	v_mul_f32_e32 v124, v124, v149
	v_mul_f32_e32 v125, v125, v157
	v_mul_f32_e32 v126, v126, v161
	v_mul_f32_e32 v127, v127, v162
	v_mul_f32_e32 v120, v120, v163
	v_mul_f32_e32 v121, v121, v166
	v_mul_f32_e32 v122, v122, v167
	v_mul_f32_e32 v115, v115, v123
	v_mul_f32_e32 v116, v116, v124
	v_mul_f32_e32 v117, v117, v125
	v_mul_f32_e32 v118, v118, v126
	v_mul_f32_e32 v119, v119, v127
	v_mul_f32_e32 v120, v112, v120
	v_mul_f32_e32 v121, v113, v121
	v_mul_f32_e32 v122, v114, v122
	v_cvt_pk_bf16_f32 v112, v116, v117
	v_cvt_pk_bf16_f32 v113, v118, v119
	v_cvt_pk_bf16_f32 v114, v120, v121
	v_cvt_pk_bf16_f32 v115, v122, v115
	global_store_dwordx4 v[158:159], v[112:115], off
	s_nop 1
	s_nop 0
	v_or_b32_e32 v112, 32, v148
	v_mad_i64_i32 v[114:115], s[38:39], v160, s56, v[144:145]
	v_lshl_add_u64 v[114:115], v[114:115], 0, v[146:147]
	v_mov_b32_e32 v113, v224
	v_fmamk_f32 v113, v113, 0x3a000000, v156
	v_rsq_f32_e32 v116, v113
	v_ashrrev_i32_e32 v113, 31, v112
	v_lshl_add_u64 v[118:119], v[112:113], 2, s[14:15]
	v_pk_mul_f32 v[106:107], v[106:107], v[116:117] op_sel_hi:[1,0]
	v_pk_mul_f32 v[110:111], v[110:111], v[116:117] op_sel_hi:[1,0]
	v_pk_mul_f32 v[108:109], v[108:109], v[116:117] op_sel_hi:[1,0]
	v_pk_mul_f32 v[104:105], v[104:105], v[116:117] op_sel_hi:[1,0]
	v_mul_f32_e32 v124, 0xbfb8aa3b, v107
	v_pk_mul_f32 v[102:103], v[102:103], v[116:117] op_sel_hi:[1,0]
	v_pk_mul_f32 v[100:101], v[100:101], v[116:117] op_sel_hi:[1,0]
	v_pk_mul_f32 v[98:99], v[98:99], v[116:117] op_sel_hi:[1,0]
	v_pk_mul_f32 v[96:97], v[96:97], v[116:117] op_sel_hi:[1,0]
	v_mul_f32_e32 v113, 0xbfb8aa3b, v108
	v_mul_f32_e32 v116, 0xbfb8aa3b, v109
	v_mul_f32_e32 v117, 0xbfb8aa3b, v110
	v_mul_f32_e32 v120, 0xbfb8aa3b, v111
	v_mul_f32_e32 v121, 0xbfb8aa3b, v104
	v_mul_f32_e32 v122, 0xbfb8aa3b, v105
	v_mul_f32_e32 v123, 0xbfb8aa3b, v106
	v_exp_f32_e32 v124, v124
	v_exp_f32_e32 v113, v113
	v_exp_f32_e32 v116, v116
	v_exp_f32_e32 v117, v117
	v_exp_f32_e32 v120, v120
	v_exp_f32_e32 v121, v121
	v_exp_f32_e32 v122, v122
	v_exp_f32_e32 v123, v123
	v_add_f32_e32 v124, 1.0, v124
	v_add_f32_e32 v113, 1.0, v113
	v_add_f32_e32 v116, 1.0, v116
	v_add_f32_e32 v117, 1.0, v117
	v_add_f32_e32 v120, 1.0, v120
	v_add_f32_e32 v121, 1.0, v121
	v_add_f32_e32 v122, 1.0, v122
	v_add_f32_e32 v123, 1.0, v123
	v_rcp_f32_e32 v124, v124
	v_rcp_f32_e32 v113, v113
	v_rcp_f32_e32 v116, v116
	v_rcp_f32_e32 v117, v117
	v_rcp_f32_e32 v120, v120
	v_rcp_f32_e32 v121, v121
	v_rcp_f32_e32 v122, v122
	v_rcp_f32_e32 v123, v123
	v_mul_f32_e32 v107, v107, v124
	v_mul_f32_e32 v108, v108, v113
	v_mul_f32_e32 v109, v109, v116
	v_mul_f32_e32 v110, v110, v117
	v_mul_f32_e32 v111, v111, v120
	v_mul_f32_e32 v104, v104, v121
	v_mul_f32_e32 v105, v105, v122
	v_mul_f32_e32 v106, v106, v123
	v_mul_f32_e32 v99, v99, v107
	v_mul_f32_e32 v100, v100, v108
	v_mul_f32_e32 v101, v101, v109
	v_mul_f32_e32 v102, v102, v110
	v_mul_f32_e32 v103, v103, v111
	v_mul_f32_e32 v104, v96, v104
	v_mul_f32_e32 v105, v97, v105
	v_mul_f32_e32 v106, v98, v106
	v_cvt_pk_bf16_f32 v96, v100, v101
	v_cvt_pk_bf16_f32 v97, v102, v103
	v_cvt_pk_bf16_f32 v98, v104, v105
	v_cvt_pk_bf16_f32 v99, v106, v99
	global_store_dwordx4 v[114:115], v[96:99], off
	s_nop 1
	s_nop 0
	v_or_b32_e32 v96, 48, v148
	v_mad_i64_i32 v[98:99], s[38:39], v112, s56, v[144:145]
	v_lshl_add_u64 v[98:99], v[98:99], 0, v[146:147]
	v_mov_b32_e32 v97, v225
	v_fmamk_f32 v97, v97, 0x3a000000, v156
	v_rsq_f32_e32 v100, v97
	v_ashrrev_i32_e32 v97, 31, v96
	v_lshl_add_u64 v[102:103], v[96:97], 2, s[14:15]
	v_pk_mul_f32 v[90:91], v[90:91], v[100:101] op_sel_hi:[1,0]
	v_pk_mul_f32 v[94:95], v[94:95], v[100:101] op_sel_hi:[1,0]
	v_pk_mul_f32 v[92:93], v[92:93], v[100:101] op_sel_hi:[1,0]
	v_pk_mul_f32 v[88:89], v[88:89], v[100:101] op_sel_hi:[1,0]
	v_mul_f32_e32 v108, 0xbfb8aa3b, v91
	v_pk_mul_f32 v[86:87], v[86:87], v[100:101] op_sel_hi:[1,0]
	v_pk_mul_f32 v[84:85], v[84:85], v[100:101] op_sel_hi:[1,0]
	v_pk_mul_f32 v[82:83], v[82:83], v[100:101] op_sel_hi:[1,0]
	v_pk_mul_f32 v[80:81], v[80:81], v[100:101] op_sel_hi:[1,0]
	v_mul_f32_e32 v97, 0xbfb8aa3b, v92
	v_mul_f32_e32 v100, 0xbfb8aa3b, v93
	v_mul_f32_e32 v101, 0xbfb8aa3b, v94
	v_mul_f32_e32 v104, 0xbfb8aa3b, v95
	v_mul_f32_e32 v105, 0xbfb8aa3b, v88
	v_mul_f32_e32 v106, 0xbfb8aa3b, v89
	v_mul_f32_e32 v107, 0xbfb8aa3b, v90
	v_exp_f32_e32 v108, v108
	v_exp_f32_e32 v97, v97
	v_exp_f32_e32 v100, v100
	v_exp_f32_e32 v101, v101
	v_exp_f32_e32 v104, v104
	v_exp_f32_e32 v105, v105
	v_exp_f32_e32 v106, v106
	v_exp_f32_e32 v107, v107
	v_add_f32_e32 v108, 1.0, v108
	v_add_f32_e32 v97, 1.0, v97
	v_add_f32_e32 v100, 1.0, v100
	v_add_f32_e32 v101, 1.0, v101
	v_add_f32_e32 v104, 1.0, v104
	v_add_f32_e32 v105, 1.0, v105
	v_add_f32_e32 v106, 1.0, v106
	v_add_f32_e32 v107, 1.0, v107
	v_rcp_f32_e32 v108, v108
	v_rcp_f32_e32 v97, v97
	v_rcp_f32_e32 v100, v100
	v_rcp_f32_e32 v101, v101
	v_rcp_f32_e32 v104, v104
	v_rcp_f32_e32 v105, v105
	v_rcp_f32_e32 v106, v106
	v_rcp_f32_e32 v107, v107
	v_mul_f32_e32 v91, v91, v108
	v_mul_f32_e32 v92, v92, v97
	v_mul_f32_e32 v93, v93, v100
	v_mul_f32_e32 v94, v94, v101
	v_mul_f32_e32 v95, v95, v104
	v_mul_f32_e32 v88, v88, v105
	v_mul_f32_e32 v89, v89, v106
	v_mul_f32_e32 v90, v90, v107
	v_mul_f32_e32 v83, v83, v91
	v_mul_f32_e32 v84, v84, v92
	v_mul_f32_e32 v85, v85, v93
	v_mul_f32_e32 v86, v86, v94
	v_mul_f32_e32 v87, v87, v95
	v_mul_f32_e32 v88, v80, v88
	v_mul_f32_e32 v89, v81, v89
	v_mul_f32_e32 v90, v82, v90
	v_cvt_pk_bf16_f32 v80, v84, v85
	v_cvt_pk_bf16_f32 v81, v86, v87
	v_cvt_pk_bf16_f32 v82, v88, v89
	v_cvt_pk_bf16_f32 v83, v90, v83
	global_store_dwordx4 v[98:99], v[80:83], off
	s_nop 1
	s_nop 0
	v_or_b32_e32 v80, 0x80, v148
	v_mad_i64_i32 v[82:83], s[38:39], v96, s56, v[144:145]
	v_lshl_add_u64 v[82:83], v[82:83], 0, v[146:147]
	v_mov_b32_e32 v81, v226
	v_fmamk_f32 v81, v81, 0x3a000000, v156
	v_rsq_f32_e32 v84, v81
	v_ashrrev_i32_e32 v81, 31, v80
	v_lshl_add_u64 v[86:87], v[80:81], 2, s[14:15]
	v_pk_mul_f32 v[74:75], v[74:75], v[84:85] op_sel_hi:[1,0]
	v_pk_mul_f32 v[78:79], v[78:79], v[84:85] op_sel_hi:[1,0]
	v_pk_mul_f32 v[76:77], v[76:77], v[84:85] op_sel_hi:[1,0]
	v_pk_mul_f32 v[72:73], v[72:73], v[84:85] op_sel_hi:[1,0]
	v_mul_f32_e32 v92, 0xbfb8aa3b, v75
	v_pk_mul_f32 v[70:71], v[70:71], v[84:85] op_sel_hi:[1,0]
	v_pk_mul_f32 v[68:69], v[68:69], v[84:85] op_sel_hi:[1,0]
	v_pk_mul_f32 v[66:67], v[66:67], v[84:85] op_sel_hi:[1,0]
	v_pk_mul_f32 v[64:65], v[64:65], v[84:85] op_sel_hi:[1,0]
	v_mul_f32_e32 v81, 0xbfb8aa3b, v76
	v_mul_f32_e32 v84, 0xbfb8aa3b, v77
	v_mul_f32_e32 v85, 0xbfb8aa3b, v78
	v_mul_f32_e32 v88, 0xbfb8aa3b, v79
	v_mul_f32_e32 v89, 0xbfb8aa3b, v72
	v_mul_f32_e32 v90, 0xbfb8aa3b, v73
	v_mul_f32_e32 v91, 0xbfb8aa3b, v74
	v_exp_f32_e32 v92, v92
	v_exp_f32_e32 v81, v81
	v_exp_f32_e32 v84, v84
	v_exp_f32_e32 v85, v85
	v_exp_f32_e32 v88, v88
	v_exp_f32_e32 v89, v89
	v_exp_f32_e32 v90, v90
	v_exp_f32_e32 v91, v91
	v_add_f32_e32 v92, 1.0, v92
	v_add_f32_e32 v81, 1.0, v81
	v_add_f32_e32 v84, 1.0, v84
	v_add_f32_e32 v85, 1.0, v85
	v_add_f32_e32 v88, 1.0, v88
	v_add_f32_e32 v89, 1.0, v89
	v_add_f32_e32 v90, 1.0, v90
	v_add_f32_e32 v91, 1.0, v91
	v_rcp_f32_e32 v92, v92
	v_rcp_f32_e32 v81, v81
	v_rcp_f32_e32 v84, v84
	v_rcp_f32_e32 v85, v85
	v_rcp_f32_e32 v88, v88
	v_rcp_f32_e32 v89, v89
	v_rcp_f32_e32 v90, v90
	v_rcp_f32_e32 v91, v91
	v_mul_f32_e32 v75, v75, v92
	v_mul_f32_e32 v76, v76, v81
	v_mul_f32_e32 v77, v77, v84
	v_mul_f32_e32 v78, v78, v85
	v_mul_f32_e32 v79, v79, v88
	v_mul_f32_e32 v72, v72, v89
	v_mul_f32_e32 v73, v73, v90
	v_mul_f32_e32 v74, v74, v91
	v_mul_f32_e32 v67, v67, v75
	v_mul_f32_e32 v68, v68, v76
	v_mul_f32_e32 v69, v69, v77
	v_mul_f32_e32 v70, v70, v78
	v_mul_f32_e32 v71, v71, v79
	v_mul_f32_e32 v72, v64, v72
	v_mul_f32_e32 v73, v65, v73
	v_mul_f32_e32 v74, v66, v74
	v_cvt_pk_bf16_f32 v64, v68, v69
	v_cvt_pk_bf16_f32 v65, v70, v71
	v_cvt_pk_bf16_f32 v66, v72, v73
	v_cvt_pk_bf16_f32 v67, v74, v67
	global_store_dwordx4 v[82:83], v[64:67], off
	s_nop 1
	s_nop 0
	v_or_b32_e32 v64, 0x90, v148
	v_mad_i64_i32 v[66:67], s[38:39], v80, s56, v[144:145]
	v_lshl_add_u64 v[66:67], v[66:67], 0, v[146:147]
	v_mov_b32_e32 v65, v227
	v_fmamk_f32 v65, v65, 0x3a000000, v156
	v_rsq_f32_e32 v68, v65
	v_ashrrev_i32_e32 v65, 31, v64
	v_lshl_add_u64 v[70:71], v[64:65], 2, s[14:15]
	v_pk_mul_f32 v[58:59], v[58:59], v[68:69] op_sel_hi:[1,0]
	v_pk_mul_f32 v[62:63], v[62:63], v[68:69] op_sel_hi:[1,0]
	v_pk_mul_f32 v[60:61], v[60:61], v[68:69] op_sel_hi:[1,0]
	v_pk_mul_f32 v[56:57], v[56:57], v[68:69] op_sel_hi:[1,0]
	v_mul_f32_e32 v76, 0xbfb8aa3b, v59
	v_pk_mul_f32 v[54:55], v[54:55], v[68:69] op_sel_hi:[1,0]
	v_pk_mul_f32 v[52:53], v[52:53], v[68:69] op_sel_hi:[1,0]
	v_pk_mul_f32 v[50:51], v[50:51], v[68:69] op_sel_hi:[1,0]
	v_pk_mul_f32 v[48:49], v[48:49], v[68:69] op_sel_hi:[1,0]
	v_mul_f32_e32 v65, 0xbfb8aa3b, v60
	v_mul_f32_e32 v68, 0xbfb8aa3b, v61
	v_mul_f32_e32 v69, 0xbfb8aa3b, v62
	v_mul_f32_e32 v72, 0xbfb8aa3b, v63
	v_mul_f32_e32 v73, 0xbfb8aa3b, v56
	v_mul_f32_e32 v74, 0xbfb8aa3b, v57
	v_mul_f32_e32 v75, 0xbfb8aa3b, v58
	v_exp_f32_e32 v76, v76
	v_exp_f32_e32 v65, v65
	v_exp_f32_e32 v68, v68
	v_exp_f32_e32 v69, v69
	v_exp_f32_e32 v72, v72
	v_exp_f32_e32 v73, v73
	v_exp_f32_e32 v74, v74
	v_exp_f32_e32 v75, v75
	v_add_f32_e32 v76, 1.0, v76
	v_add_f32_e32 v65, 1.0, v65
	v_add_f32_e32 v68, 1.0, v68
	v_add_f32_e32 v69, 1.0, v69
	v_add_f32_e32 v72, 1.0, v72
	v_add_f32_e32 v73, 1.0, v73
	v_add_f32_e32 v74, 1.0, v74
	v_add_f32_e32 v75, 1.0, v75
	v_rcp_f32_e32 v76, v76
	v_rcp_f32_e32 v65, v65
	v_rcp_f32_e32 v68, v68
	v_rcp_f32_e32 v69, v69
	v_rcp_f32_e32 v72, v72
	v_rcp_f32_e32 v73, v73
	v_rcp_f32_e32 v74, v74
	v_rcp_f32_e32 v75, v75
	v_mul_f32_e32 v59, v59, v76
	v_mul_f32_e32 v60, v60, v65
	v_mul_f32_e32 v61, v61, v68
	v_mul_f32_e32 v62, v62, v69
	v_mul_f32_e32 v63, v63, v72
	v_mul_f32_e32 v56, v56, v73
	v_mul_f32_e32 v57, v57, v74
	v_mul_f32_e32 v58, v58, v75
	v_mul_f32_e32 v51, v51, v59
	v_mul_f32_e32 v52, v52, v60
	v_mul_f32_e32 v53, v53, v61
	v_mul_f32_e32 v54, v54, v62
	v_mul_f32_e32 v55, v55, v63
	v_mul_f32_e32 v56, v48, v56
	v_mul_f32_e32 v57, v49, v57
	v_mul_f32_e32 v58, v50, v58
	v_cvt_pk_bf16_f32 v48, v52, v53
	v_cvt_pk_bf16_f32 v49, v54, v55
	v_cvt_pk_bf16_f32 v50, v56, v57
	v_cvt_pk_bf16_f32 v51, v58, v51
	global_store_dwordx4 v[66:67], v[48:51], off
	s_nop 1
	s_nop 0
	v_or_b32_e32 v48, 0xa0, v148
	v_mad_i64_i32 v[50:51], s[38:39], v64, s56, v[144:145]
	v_lshl_add_u64 v[50:51], v[50:51], 0, v[146:147]
	v_mov_b32_e32 v49, v228
	v_fmamk_f32 v49, v49, 0x3a000000, v156
	v_rsq_f32_e32 v52, v49
	v_ashrrev_i32_e32 v49, 31, v48
	v_lshl_add_u64 v[54:55], v[48:49], 2, s[14:15]
	v_pk_mul_f32 v[42:43], v[42:43], v[52:53] op_sel_hi:[1,0]
	v_pk_mul_f32 v[46:47], v[46:47], v[52:53] op_sel_hi:[1,0]
	v_pk_mul_f32 v[44:45], v[44:45], v[52:53] op_sel_hi:[1,0]
	v_pk_mul_f32 v[40:41], v[40:41], v[52:53] op_sel_hi:[1,0]
	v_mul_f32_e32 v60, 0xbfb8aa3b, v43
	v_pk_mul_f32 v[38:39], v[38:39], v[52:53] op_sel_hi:[1,0]
	v_pk_mul_f32 v[36:37], v[36:37], v[52:53] op_sel_hi:[1,0]
	v_pk_mul_f32 v[34:35], v[34:35], v[52:53] op_sel_hi:[1,0]
	v_pk_mul_f32 v[32:33], v[32:33], v[52:53] op_sel_hi:[1,0]
	v_mul_f32_e32 v49, 0xbfb8aa3b, v44
	v_mul_f32_e32 v52, 0xbfb8aa3b, v45
	v_mul_f32_e32 v53, 0xbfb8aa3b, v46
	v_mul_f32_e32 v56, 0xbfb8aa3b, v47
	v_mul_f32_e32 v57, 0xbfb8aa3b, v40
	v_mul_f32_e32 v58, 0xbfb8aa3b, v41
	v_mul_f32_e32 v59, 0xbfb8aa3b, v42
	v_exp_f32_e32 v60, v60
	v_exp_f32_e32 v49, v49
	v_exp_f32_e32 v52, v52
	v_exp_f32_e32 v53, v53
	v_exp_f32_e32 v56, v56
	v_exp_f32_e32 v57, v57
	v_exp_f32_e32 v58, v58
	v_exp_f32_e32 v59, v59
	v_add_f32_e32 v60, 1.0, v60
	v_add_f32_e32 v49, 1.0, v49
	v_add_f32_e32 v52, 1.0, v52
	v_add_f32_e32 v53, 1.0, v53
	v_add_f32_e32 v56, 1.0, v56
	v_add_f32_e32 v57, 1.0, v57
	v_add_f32_e32 v58, 1.0, v58
	v_add_f32_e32 v59, 1.0, v59
	v_rcp_f32_e32 v60, v60
	v_rcp_f32_e32 v49, v49
	v_rcp_f32_e32 v52, v52
	v_rcp_f32_e32 v53, v53
	v_rcp_f32_e32 v56, v56
	v_rcp_f32_e32 v57, v57
	v_rcp_f32_e32 v58, v58
	v_rcp_f32_e32 v59, v59
	v_mul_f32_e32 v43, v43, v60
	v_mul_f32_e32 v44, v44, v49
	v_mul_f32_e32 v45, v45, v52
	v_mul_f32_e32 v46, v46, v53
	v_mul_f32_e32 v47, v47, v56
	v_mul_f32_e32 v40, v40, v57
	v_mul_f32_e32 v41, v41, v58
	v_mul_f32_e32 v42, v42, v59
	v_mul_f32_e32 v35, v35, v43
	v_mul_f32_e32 v36, v36, v44
	v_mul_f32_e32 v37, v37, v45
	v_mul_f32_e32 v38, v38, v46
	v_mul_f32_e32 v39, v39, v47
	v_mul_f32_e32 v40, v32, v40
	v_mul_f32_e32 v41, v33, v41
	v_mul_f32_e32 v42, v34, v42
	v_cvt_pk_bf16_f32 v32, v36, v37
	v_cvt_pk_bf16_f32 v33, v38, v39
	v_cvt_pk_bf16_f32 v34, v40, v41
	v_cvt_pk_bf16_f32 v35, v42, v35
	global_store_dwordx4 v[50:51], v[32:35], off
	s_nop 1
	s_nop 0
	v_or_b32_e32 v32, 0xb0, v148
	v_mad_i64_i32 v[34:35], s[38:39], v48, s56, v[144:145]
	v_lshl_add_u64 v[34:35], v[34:35], 0, v[146:147]
	v_mov_b32_e32 v33, v229
	v_fmamk_f32 v33, v33, 0x3a000000, v156
	v_rsq_f32_e32 v36, v33
	v_ashrrev_i32_e32 v33, 31, v32
	v_lshl_add_u64 v[38:39], v[32:33], 2, s[14:15]
	v_pk_mul_f32 v[26:27], v[26:27], v[36:37] op_sel_hi:[1,0]
	v_pk_mul_f32 v[30:31], v[30:31], v[36:37] op_sel_hi:[1,0]
	v_pk_mul_f32 v[28:29], v[28:29], v[36:37] op_sel_hi:[1,0]
	v_pk_mul_f32 v[24:25], v[24:25], v[36:37] op_sel_hi:[1,0]
	v_mul_f32_e32 v44, 0xbfb8aa3b, v27
	v_pk_mul_f32 v[22:23], v[22:23], v[36:37] op_sel_hi:[1,0]
	v_pk_mul_f32 v[20:21], v[20:21], v[36:37] op_sel_hi:[1,0]
	v_pk_mul_f32 v[18:19], v[18:19], v[36:37] op_sel_hi:[1,0]
	v_pk_mul_f32 v[16:17], v[16:17], v[36:37] op_sel_hi:[1,0]
	v_mul_f32_e32 v33, 0xbfb8aa3b, v28
	v_mul_f32_e32 v36, 0xbfb8aa3b, v29
	v_mul_f32_e32 v37, 0xbfb8aa3b, v30
	v_mul_f32_e32 v40, 0xbfb8aa3b, v31
	v_mul_f32_e32 v41, 0xbfb8aa3b, v24
	v_mul_f32_e32 v42, 0xbfb8aa3b, v25
	v_mul_f32_e32 v43, 0xbfb8aa3b, v26
	v_exp_f32_e32 v44, v44
	v_exp_f32_e32 v33, v33
	v_exp_f32_e32 v36, v36
	v_exp_f32_e32 v37, v37
	v_exp_f32_e32 v40, v40
	v_exp_f32_e32 v41, v41
	v_exp_f32_e32 v42, v42
	v_exp_f32_e32 v43, v43
	v_add_f32_e32 v44, 1.0, v44
	v_add_f32_e32 v33, 1.0, v33
	v_add_f32_e32 v36, 1.0, v36
	v_add_f32_e32 v37, 1.0, v37
	v_add_f32_e32 v40, 1.0, v40
	v_add_f32_e32 v41, 1.0, v41
	v_add_f32_e32 v42, 1.0, v42
	v_add_f32_e32 v43, 1.0, v43
	v_rcp_f32_e32 v44, v44
	v_rcp_f32_e32 v33, v33
	v_rcp_f32_e32 v36, v36
	v_rcp_f32_e32 v37, v37
	v_rcp_f32_e32 v40, v40
	v_rcp_f32_e32 v41, v41
	v_rcp_f32_e32 v42, v42
	v_rcp_f32_e32 v43, v43
	v_mul_f32_e32 v27, v27, v44
	v_mul_f32_e32 v28, v28, v33
	v_mul_f32_e32 v29, v29, v36
	v_mul_f32_e32 v30, v30, v37
	v_mul_f32_e32 v31, v31, v40
	v_mul_f32_e32 v24, v24, v41
	v_mul_f32_e32 v25, v25, v42
	v_mul_f32_e32 v26, v26, v43
	v_mul_f32_e32 v19, v19, v27
	v_mul_f32_e32 v20, v20, v28
	v_mul_f32_e32 v21, v21, v29
	v_mul_f32_e32 v22, v22, v30
	v_mul_f32_e32 v23, v23, v31
	v_mul_f32_e32 v24, v16, v24
	v_mul_f32_e32 v25, v17, v25
	v_mul_f32_e32 v26, v18, v26
	v_cvt_pk_bf16_f32 v16, v20, v21
	v_cvt_pk_bf16_f32 v17, v22, v23
	v_cvt_pk_bf16_f32 v18, v24, v25
	v_cvt_pk_bf16_f32 v19, v26, v19
	global_store_dwordx4 v[34:35], v[16:19], off
	s_nop 1
	s_nop 0
	v_mad_i64_i32 v[18:19], s[38:39], v32, s56, v[144:145]
	v_lshl_add_u64 v[18:19], v[18:19], 0, v[146:147]
	v_mov_b32_e32 v16, v230
	v_fmamk_f32 v16, v16, 0x3a000000, v156
	v_rsq_f32_e32 v16, v16
	s_nop 0
	v_pk_mul_f32 v[10:11], v[10:11], v[16:17] op_sel_hi:[1,0]
	v_pk_mul_f32 v[14:15], v[14:15], v[16:17] op_sel_hi:[1,0]
	v_pk_mul_f32 v[12:13], v[12:13], v[16:17] op_sel_hi:[1,0]
	v_pk_mul_f32 v[8:9], v[8:9], v[16:17] op_sel_hi:[1,0]
	v_mul_f32_e32 v25, 0xbfb8aa3b, v11
	v_pk_mul_f32 v[6:7], v[6:7], v[16:17] op_sel_hi:[1,0]
	v_pk_mul_f32 v[4:5], v[4:5], v[16:17] op_sel_hi:[1,0]
	v_pk_mul_f32 v[2:3], v[2:3], v[16:17] op_sel_hi:[1,0]
	v_pk_mul_f32 v[0:1], v[0:1], v[16:17] op_sel_hi:[1,0]
	v_mul_f32_e32 v16, 0xbfb8aa3b, v12
	v_mul_f32_e32 v17, 0xbfb8aa3b, v13
	v_mul_f32_e32 v20, 0xbfb8aa3b, v14
	v_mul_f32_e32 v21, 0xbfb8aa3b, v15
	v_mul_f32_e32 v22, 0xbfb8aa3b, v8
	v_mul_f32_e32 v23, 0xbfb8aa3b, v9
	v_mul_f32_e32 v24, 0xbfb8aa3b, v10
	v_exp_f32_e32 v25, v25
	v_exp_f32_e32 v16, v16
	v_exp_f32_e32 v17, v17
	v_exp_f32_e32 v20, v20
	v_exp_f32_e32 v21, v21
	v_exp_f32_e32 v22, v22
	v_exp_f32_e32 v23, v23
	v_exp_f32_e32 v24, v24
	v_add_f32_e32 v25, 1.0, v25
	v_add_f32_e32 v16, 1.0, v16
	v_add_f32_e32 v17, 1.0, v17
	v_add_f32_e32 v20, 1.0, v20
	v_add_f32_e32 v21, 1.0, v21
	v_add_f32_e32 v22, 1.0, v22
	v_add_f32_e32 v23, 1.0, v23
	v_add_f32_e32 v24, 1.0, v24
	v_rcp_f32_e32 v25, v25
	v_rcp_f32_e32 v16, v16
	v_rcp_f32_e32 v17, v17
	v_rcp_f32_e32 v20, v20
	v_rcp_f32_e32 v21, v21
	v_rcp_f32_e32 v22, v22
	v_rcp_f32_e32 v23, v23
	v_rcp_f32_e32 v24, v24
	v_mul_f32_e32 v11, v11, v25
	v_mul_f32_e32 v12, v12, v16
	v_mul_f32_e32 v13, v13, v17
	v_mul_f32_e32 v14, v14, v20
	v_mul_f32_e32 v15, v15, v21
	v_mul_f32_e32 v8, v8, v22
	v_mul_f32_e32 v9, v9, v23
	v_mul_f32_e32 v10, v10, v24
	v_mul_f32_e32 v3, v3, v11
	v_mul_f32_e32 v4, v4, v12
	v_mul_f32_e32 v5, v5, v13
	v_mul_f32_e32 v6, v6, v14
	v_mul_f32_e32 v7, v7, v15
	v_mul_f32_e32 v8, v0, v8
	v_mul_f32_e32 v9, v1, v9
	v_mul_f32_e32 v10, v2, v10
	v_cvt_pk_bf16_f32 v0, v4, v5
	v_cvt_pk_bf16_f32 v1, v6, v7
	v_cvt_pk_bf16_f32 v2, v8, v9
	v_cvt_pk_bf16_f32 v3, v10, v3
	global_store_dwordx4 v[18:19], v[0:3], off
	s_cbranch_vccnz .LBB0_1236
	s_andn2_b64 vcc, exec, s[8:9]
	s_cbranch_vccnz .LBB0_1235
	s_barrier
	s_branch .LBB0_1235
